# attention steady loop: value-preserving VALU trims (fold the +0.0 adds, drop self-max canonicalisations around the row-max) on top of v11
# speedup vs baseline: 1.0008x; 1.0008x over previous
.LBB0_1341:
	v_sub_f32_e32 v0, v214, v217
	s_waitcnt lgkmcnt(4)
	v_sub_f32_e32 v111, v0, v223
	v_sub_f32_e32 v110, v0, v222
	v_sub_f32_e32 v109, v0, v221
	v_sub_f32_e32 v108, v0, v220
	v_sub_f32_e32 v107, v0, v199
	v_sub_f32_e32 v106, v0, v198
	v_sub_f32_e32 v105, v0, v197
	v_sub_f32_e32 v104, v0, v196
	v_sub_f32_e32 v103, v0, v195
	v_sub_f32_e32 v102, v0, v194
	v_sub_f32_e32 v101, v0, v193
	v_sub_f32_e32 v100, v0, v192
	v_sub_f32_e32 v99, v0, v191
	v_sub_f32_e32 v98, v0, v190
	v_sub_f32_e32 v97, v0, v189
	v_sub_f32_e32 v96, v0, v188
	s_waitcnt lgkmcnt(0)
	v_sub_f32_e32 v95, v0, v239
	v_sub_f32_e32 v94, v0, v238
	v_sub_f32_e32 v93, v0, v237
	v_sub_f32_e32 v92, v0, v236
	v_sub_f32_e32 v91, v0, v235
	v_sub_f32_e32 v90, v0, v234
	v_sub_f32_e32 v89, v0, v233
	v_sub_f32_e32 v88, v0, v232
	v_sub_f32_e32 v87, v0, v231
	v_sub_f32_e32 v86, v0, v230
	v_sub_f32_e32 v85, v0, v229
	v_sub_f32_e32 v84, v0, v228
	v_sub_f32_e32 v83, v0, v227
	v_sub_f32_e32 v82, v0, v226
	v_sub_f32_e32 v81, v0, v225
	v_sub_f32_e32 v80, v0, v224
	ds_read_b128 v[188:191], v180 offset:256
	ds_read_b128 v[192:195], v180 offset:288
	ds_read_b128 v[196:199], v180 offset:320
	ds_read_b128 v[220:223], v180 offset:352
	ds_read_b128 v[224:227], v180 offset:384
	ds_read_b128 v[228:231], v180 offset:416
	ds_read_b128 v[232:235], v180 offset:448
	ds_read_b128 v[236:239], v180 offset:480
	v_add_u32_e32 v0, s8, v216
	ds_read_b64_tr_b16 v[4:5], v0 offset:24576
	ds_read_b64_tr_b16 v[6:7], v0 offset:25088
	v_mfma_f32_32x32x16_bf16 v[96:111], v[172:175], v[124:127], v[96:111]
	v_add_f32_e32 v1, v64, v65
	v_add_f32_e32 v1, v66, v1
	v_add_f32_e32 v1, v67, v1
	v_add_f32_e32 v1, v68, v1
	v_add_f32_e32 v1, v69, v1
	v_cvt_pk_bf16_f32 v140, v64, v65
	v_cvt_pk_bf16_f32 v141, v66, v67
	ds_read_b64_tr_b16 v[8:9], v0 offset:28672
	ds_read_b64_tr_b16 v[10:11], v0 offset:29184
	v_mfma_f32_32x32x16_bf16 v[80:95], v[168:171], v[124:127], v[80:95]
	v_add_f32_e32 v1, v70, v1
	v_add_f32_e32 v1, v71, v1
	v_add_f32_e32 v1, v72, v1
	v_add_f32_e32 v1, v73, v1
	v_cvt_pk_bf16_f32 v142, v68, v69
	v_cvt_pk_bf16_f32 v143, v70, v71
	ds_read_b64_tr_b16 v[12:13], v0 offset:25600
	ds_read_b64_tr_b16 v[14:15], v0 offset:26112
	v_mfma_f32_32x32x16_bf16 v[96:111], v[164:167], v[120:123], v[96:111]
	v_add_f32_e32 v1, v74, v1
	v_add_f32_e32 v1, v75, v1
	v_add_f32_e32 v1, v76, v1
	v_add_f32_e32 v1, v77, v1
	v_cvt_pk_bf16_f32 v136, v72, v73
	v_cvt_pk_bf16_f32 v137, v74, v75
	ds_read_b64_tr_b16 v[64:65], v0 offset:29696
	ds_read_b64_tr_b16 v[66:67], v0 offset:30208
	v_mfma_f32_32x32x16_bf16 v[80:95], v[160:163], v[120:123], v[80:95]
	v_add_f32_e32 v1, v78, v1
	v_add_f32_e32 v1, v79, v1
	v_add_f32_e32 v1, v48, v1
	v_add_f32_e32 v1, v49, v1
	v_cvt_pk_bf16_f32 v138, v76, v77
	v_cvt_pk_bf16_f32 v139, v78, v79
	ds_read_b64_tr_b16 v[68:69], v0 offset:26624
	ds_read_b64_tr_b16 v[70:71], v0 offset:27136
	v_mfma_f32_32x32x16_bf16 v[96:111], v[156:159], v[116:119], v[96:111]
	v_add_f32_e32 v1, v50, v1
	v_add_f32_e32 v1, v51, v1
	v_add_f32_e32 v1, v52, v1
	v_add_f32_e32 v1, v53, v1
	v_cvt_pk_bf16_f32 v132, v48, v49
	v_cvt_pk_bf16_f32 v133, v50, v51
	ds_read_b64_tr_b16 v[48:49], v0 offset:30720
	ds_read_b64_tr_b16 v[50:51], v0 offset:31232
	v_mfma_f32_32x32x16_bf16 v[80:95], v[152:155], v[116:119], v[80:95]
	v_add_f32_e32 v1, v54, v1
	v_add_f32_e32 v1, v55, v1
	v_add_f32_e32 v1, v56, v1
	v_add_f32_e32 v1, v57, v1
	v_cvt_pk_bf16_f32 v134, v52, v53
	v_cvt_pk_bf16_f32 v135, v54, v55
	ds_read_b64_tr_b16 v[52:53], v0 offset:27648
	ds_read_b64_tr_b16 v[54:55], v0 offset:28160
	v_mfma_f32_32x32x16_bf16 v[96:111], v[148:151], v[112:115], v[96:111]
	v_add_f32_e32 v1, v58, v1
	v_add_f32_e32 v1, v59, v1
	v_add_f32_e32 v1, v60, v1
	v_add_f32_e32 v1, v61, v1
	v_cvt_pk_bf16_f32 v128, v56, v57
	v_cvt_pk_bf16_f32 v129, v58, v59
	ds_read_b64_tr_b16 v[56:57], v0 offset:31744
	ds_read_b64_tr_b16 v[58:59], v0 offset:32256
	v_mfma_f32_32x32x16_bf16 v[80:95], v[144:147], v[112:115], v[80:95]
	v_add_f32_e32 v0, v62, v1
	v_add_f32_e32 v2, v63, v0
	v_cvt_pk_bf16_f32 v130, v60, v61
	v_cvt_pk_bf16_f32 v131, v62, v63
	s_mov_b32 s8, 0xfffe0000
	s_mov_b32 s9, -1
	v_lshl_add_u64 v[0:1], v[178:179], 0, s[8:9]
	s_add_i32 s0, s16, s21
	s_mov_b32 s4, m0
	s_mov_b32 m0, s0
	s_nop 0
	global_load_lds_dwordx4 v[0:1], off
	s_mov_b32 m0, s4
	v_lshl_add_u64 v[0:1], v[176:177], 0, s[8:9]
	s_add_i32 s0, s14, s22
	s_mov_b32 s4, m0
	s_mov_b32 m0, s0
	s_nop 0
	global_load_lds_dwordx4 v[0:1], off
	s_mov_b32 m0, s4
	v_max_f32_e32 v0, v96, v97
	v_max3_f32 v1, v98, v99, v81
	v_max3_f32 v0, v0, v80, v82
	v_max3_f32 v0, v0, v83, v100
	v_max3_f32 v1, v1, v102, v103
	v_max3_f32 v0, v0, v101, v84
	v_max3_f32 v1, v1, v86, v87
	v_max3_f32 v0, v0, v85, v104
	v_max3_f32 v1, v1, v106, v107
	v_max3_f32 v0, v0, v105, v88
	v_max3_f32 v1, v1, v90, v91
	v_max3_f32 v0, v0, v89, v108
	v_max3_f32 v1, v1, v110, v111
	v_max3_f32 v60, v0, v109, v92
	v_max3_f32 v1, v1, v94, v95
	v_max3_f32 v1, v60, v93, v1
	v_add_f32_e32 v0, v218, v2
	v_mov_b32_e32 v2, v1
	s_nop 1
	v_permlane32_swap_b32_e32 v1, v2
	v_max_f32_e32 v1, v1, v2
	v_cmp_lt_f32_e32 vcc, s33, v1
	s_cmp_lg_u64 vcc, 0
	s_cselect_b64 s[8:9], -1, 0
	s_cbranch_vccnz .LBB0_1349

.LBB0_1344:
	s_add_i32 s0, s14, 0x2000
	s_cmpk_lg_i32 s14, 0x4000
	s_cselect_b32 s25, s0, 0
	v_sub_f32_e32 v1, v214, v217
	s_waitcnt lgkmcnt(4)
	v_sub_f32_e32 v79, v1, v223
	v_sub_f32_e32 v78, v1, v222
	v_sub_f32_e32 v77, v1, v221
	v_sub_f32_e32 v76, v1, v220
	v_sub_f32_e32 v75, v1, v199
	v_sub_f32_e32 v74, v1, v198
	v_sub_f32_e32 v73, v1, v197
	v_sub_f32_e32 v72, v1, v196
	v_sub_f32_e32 v71, v1, v195
	v_sub_f32_e32 v70, v1, v194
	v_sub_f32_e32 v69, v1, v193
	v_sub_f32_e32 v68, v1, v192
	v_sub_f32_e32 v67, v1, v191
	v_sub_f32_e32 v66, v1, v190
	v_sub_f32_e32 v65, v1, v189
	v_sub_f32_e32 v64, v1, v188
	s_waitcnt lgkmcnt(0)
	v_sub_f32_e32 v63, v1, v239
	v_sub_f32_e32 v62, v1, v238
	v_sub_f32_e32 v61, v1, v237
	v_sub_f32_e32 v60, v1, v236
	v_sub_f32_e32 v59, v1, v235
	v_sub_f32_e32 v58, v1, v234
	v_sub_f32_e32 v57, v1, v233
	v_sub_f32_e32 v56, v1, v232
	v_sub_f32_e32 v55, v1, v231
	v_sub_f32_e32 v54, v1, v230
	v_sub_f32_e32 v53, v1, v229
	v_sub_f32_e32 v52, v1, v228
	v_sub_f32_e32 v51, v1, v227
	v_sub_f32_e32 v50, v1, v226
	v_sub_f32_e32 v49, v1, v225
	v_sub_f32_e32 v48, v1, v224
	ds_read_b128 v[188:191], v180 offset:512
	ds_read_b128 v[192:195], v180 offset:544
	ds_read_b128 v[196:199], v180 offset:576
	ds_read_b128 v[220:223], v180 offset:608
	ds_read_b128 v[224:227], v180 offset:640
	ds_read_b128 v[228:231], v180 offset:672
	ds_read_b128 v[232:235], v180 offset:704
	ds_read_b128 v[236:239], v180 offset:736
	v_add_u32_e32 v1, s16, v216
	ds_read_b64_tr_b16 v[152:153], v1 offset:24576
	ds_read_b64_tr_b16 v[154:155], v1 offset:25088
	v_mfma_f32_32x32x16_bf16 v[64:79], v[164:167], v[124:127], v[64:79]
	v_add_f32_e32 v2, v96, v97
	v_add_f32_e32 v2, v98, v2
	v_add_f32_e32 v2, v99, v2
	v_add_f32_e32 v2, v100, v2
	v_add_f32_e32 v2, v101, v2
	v_cvt_pk_bf16_f32 v140, v96, v97
	v_cvt_pk_bf16_f32 v141, v98, v99
	ds_read_b64_tr_b16 v[96:97], v1 offset:28672
	ds_read_b64_tr_b16 v[98:99], v1 offset:29184
	v_mfma_f32_32x32x16_bf16 v[48:63], v[160:163], v[124:127], v[48:63]
	v_add_f32_e32 v2, v102, v2
	v_add_f32_e32 v2, v103, v2
	v_add_f32_e32 v2, v104, v2
	v_add_f32_e32 v2, v105, v2
	v_cvt_pk_bf16_f32 v142, v100, v101
	v_cvt_pk_bf16_f32 v143, v102, v103
	ds_read_b64_tr_b16 v[100:101], v1 offset:25600
	ds_read_b64_tr_b16 v[102:103], v1 offset:26112
	v_mfma_f32_32x32x16_bf16 v[64:79], v[156:159], v[120:123], v[64:79]
	v_add_f32_e32 v2, v106, v2
	v_add_f32_e32 v2, v107, v2
	v_add_f32_e32 v2, v108, v2
	v_add_f32_e32 v2, v109, v2
	v_cvt_pk_bf16_f32 v136, v104, v105
	v_cvt_pk_bf16_f32 v137, v106, v107
	ds_read_b64_tr_b16 v[104:105], v1 offset:29696
	ds_read_b64_tr_b16 v[106:107], v1 offset:30208
	v_mfma_f32_32x32x16_bf16 v[48:63], v[148:151], v[120:123], v[48:63]
	v_add_f32_e32 v2, v110, v2
	v_add_f32_e32 v2, v111, v2
	v_add_f32_e32 v2, v80, v2
	v_add_f32_e32 v2, v81, v2
	v_cvt_pk_bf16_f32 v138, v108, v109
	v_cvt_pk_bf16_f32 v139, v110, v111
	ds_read_b64_tr_b16 v[108:109], v1 offset:26624
	ds_read_b64_tr_b16 v[110:111], v1 offset:27136
	v_mfma_f32_32x32x16_bf16 v[64:79], v[144:147], v[116:119], v[64:79]
	v_add_f32_e32 v2, v82, v2
	v_add_f32_e32 v2, v83, v2
	v_add_f32_e32 v2, v84, v2
	v_add_f32_e32 v2, v85, v2
	v_cvt_pk_bf16_f32 v132, v80, v81
	v_cvt_pk_bf16_f32 v133, v82, v83
	ds_read_b64_tr_b16 v[80:81], v1 offset:30720
	ds_read_b64_tr_b16 v[82:83], v1 offset:31232
	v_mfma_f32_32x32x16_bf16 v[48:63], v[12:15], v[116:119], v[48:63]
	v_add_f32_e32 v2, v86, v2
	v_add_f32_e32 v2, v87, v2
	v_add_f32_e32 v2, v88, v2
	v_add_f32_e32 v2, v89, v2
	v_cvt_pk_bf16_f32 v134, v84, v85
	v_cvt_pk_bf16_f32 v135, v86, v87
	ds_read_b64_tr_b16 v[12:13], v1 offset:27648
	ds_read_b64_tr_b16 v[14:15], v1 offset:28160
	v_mfma_f32_32x32x16_bf16 v[64:79], v[8:11], v[112:115], v[64:79]
	v_add_f32_e32 v2, v90, v2
	v_add_f32_e32 v2, v91, v2
	v_add_f32_e32 v2, v92, v2
	v_add_f32_e32 v2, v93, v2
	v_cvt_pk_bf16_f32 v128, v88, v89
	v_cvt_pk_bf16_f32 v129, v90, v91
	ds_read_b64_tr_b16 v[8:9], v1 offset:31744
	ds_read_b64_tr_b16 v[10:11], v1 offset:32256
	v_mfma_f32_32x32x16_bf16 v[48:63], v[4:7], v[112:115], v[48:63]
	v_add_f32_e32 v1, v94, v2
	v_add_f32_e32 v1, v95, v1
	v_cvt_pk_bf16_f32 v130, v92, v93
	v_cvt_pk_bf16_f32 v131, v94, v95
	v_max_f32_e32 v2, v64, v65
	s_nop 6
	v_max3_f32 v4, v66, v67, v49
	v_max3_f32 v2, v2, v48, v50
	v_max3_f32 v2, v2, v51, v68
	v_max3_f32 v4, v4, v70, v71
	v_max3_f32 v2, v2, v69, v52
	v_max3_f32 v4, v4, v54, v55
	v_max3_f32 v2, v2, v53, v72
	v_max3_f32 v4, v4, v74, v75
	v_max3_f32 v2, v2, v73, v56
	v_max3_f32 v4, v4, v58, v59
	v_max3_f32 v2, v2, v57, v76
	v_max3_f32 v4, v4, v78, v79
	v_max3_f32 v2, v2, v77, v60
	v_max3_f32 v4, v4, v62, v63
	v_add_f32_e32 v218, v0, v1
	v_max3_f32 v0, v2, v61, v4
	v_mov_b32_e32 v1, v0
	s_nop 1
	v_permlane32_swap_b32_e32 v0, v1
	s_add_i32 s0, s14, s21
	s_mov_b32 s4, m0
	s_mov_b32 m0, s0
	s_nop 0
	global_load_lds_dwordx4 v[178:179], off
	s_mov_b32 m0, s4
	v_max_f32_e32 v0, v0, v1
	s_add_i32 s0, s25, s22
	s_mov_b32 s4, m0
	s_mov_b32 m0, s0
	s_nop 0
	global_load_lds_dwordx4 v[176:177], off
	s_mov_b32 m0, s4
	v_cmp_lt_f32_e32 vcc, s33, v0
	s_cmp_lg_u64 vcc, 0
	s_cselect_b64 s[8:9], -1, 0
	s_cbranch_vccnz .LBB0_1352
